# phase A tile order: WGs 0-127 run their extra (7th-round) tile first while WGs 128-255 convert weights, then all WGs run rounds 0-5 in lockstep
# speedup vs baseline: 1.0021x; 1.0021x over previous
.LBB0_256:
	v_writelane_b32 v252, s34, 41
	s_nop 1
	v_writelane_b32 v252, s35, 42
	s_or_b64 exec, exec, s[0:1]
	s_add_u32 s0, s28, 0x9980000
	s_addc_u32 s1, s29, 0
	v_writelane_b32 v252, s0, 43
	s_mul_i32 s31, s31, s30
	v_mov_b32_e32 v161, 0
	v_writelane_b32 v252, s1, 44
	s_lshl_b32 s0, s30, 3
	v_writelane_b32 v252, s0, 45
	s_add_i32 s0, s2, 0x730
	s_cmpk_lt_i32 s0, 0xb30
	v_writelane_b32 v252, s0, 46
	s_cselect_b64 s[0:1], -1, 0
	v_writelane_b32 v252, s0, 47
	v_mov_b32_e32 v245, 1
	v_mov_b32_e32 v246, 0x358637bd
	v_writelane_b32 v252, s1, 48
	s_add_u32 s0, s28, 0xb980000
	s_addc_u32 s1, s29, 0
	v_writelane_b32 v252, s0, 49
	v_mov_b64_e32 v[162:163], 0x3ff
	v_mov_b64_e32 v[164:165], 0x400
	v_writelane_b32 v252, s1, 50
	s_add_u32 s0, s28, 0x9180000
	s_addc_u32 s1, s29, 0
	v_writelane_b32 v252, s0, 51
	v_mov_b64_e32 v[166:167], 0xfff
	v_mov_b64_e32 v[168:169], 0x1000
	v_writelane_b32 v252, s1, 52
	s_add_u32 s0, s28, 0x9080000
	v_writelane_b32 v252, s0, 53
	s_addc_u32 s0, s29, 0
	v_writelane_b32 v252, s0, 54
	s_add_u32 s0, s28, 0x8e80000
	s_addc_u32 s1, s29, 0
	v_writelane_b32 v252, s0, 55
	s_movk_i32 s63, 0x2000
	s_mov_b32 s89, 0x40000
	v_writelane_b32 v252, s1, 56
	s_add_u32 s0, s28, 0x8d00000
	s_addc_u32 s1, s29, 0
	s_add_u32 s38, s28, 0x8000000
	s_addc_u32 s39, s29, 0
	v_writelane_b32 v252, s0, 57
	s_cmp_lg_u64 s[74:75], 0
	s_mov_b32 s95, 0xa000
	v_writelane_b32 v252, s1, 58
	s_cselect_b64 s[0:1], -1, 0
	v_writelane_b32 v252, s0, 59
	s_movk_i32 s91, 0xc00
	s_mov_b32 s90, 0x42ddb3d8
	v_writelane_b32 v252, s1, 60
	v_writelane_b32 v252, s64, 61
	s_cmp_lg_u64 s[66:67], 0
	s_cselect_b64 s[0:1], -1, 0
	v_writelane_b32 v253, s67, 0
	v_writelane_b32 v253, s68, 1
	v_writelane_b32 v253, s69, 2
	v_writelane_b32 v253, s70, 3
	v_writelane_b32 v253, s71, 4
	v_writelane_b32 v253, s72, 5
	v_writelane_b32 v253, s73, 6
	v_writelane_b32 v252, s65, 62
	v_writelane_b32 v253, s74, 7
	v_writelane_b32 v252, s66, 63
	v_writelane_b32 v253, s75, 8
	v_writelane_b32 v253, s76, 9
	v_readlane_b32 s4, v252, 22
	v_writelane_b32 v253, s77, 10
	v_readlane_b32 s5, v252, 23
	v_readlane_b32 s6, v252, 24
	v_readlane_b32 s7, v252, 25
	v_readlane_b32 s8, v252, 26
	v_readlane_b32 s9, v252, 27
	v_readlane_b32 s10, v252, 28
	v_readlane_b32 s11, v252, 29
	v_readlane_b32 s12, v252, 30
	v_readlane_b32 s13, v252, 31
	v_readlane_b32 s14, v252, 32
	v_readlane_b32 s15, v252, 33
	v_writelane_b32 v253, s78, 11
	v_readlane_b32 s16, v252, 34
	v_readlane_b32 s17, v252, 35
	v_readlane_b32 s18, v252, 36
	v_readlane_b32 s19, v252, 37
	s_mov_b64 s[4:5], s[8:9]
	v_writelane_b32 v253, s79, 12
	s_mov_b64 s[6:7], s[10:11]
	s_mov_b64 s[8:9], s[12:13]
	s_mov_b64 s[10:11], s[14:15]
	s_mov_b64 s[12:13], s[16:17]
	v_writelane_b32 v253, s0, 13
	s_cmp_lg_u64 s[12:13], 0
	s_mov_b64 s[14:15], s[18:19]
	v_writelane_b32 v253, s1, 14
	s_cselect_b64 s[0:1], -1, 0
	v_writelane_b32 v253, s0, 15
	s_cmp_lg_u64 s[10:11], 0
	s_mov_b64 s[92:93], 0x80
	v_writelane_b32 v253, s1, 16
	s_cselect_b64 s[0:1], -1, 0
	s_ashr_i32 s3, s2, 31
	v_writelane_b32 v253, s0, 17
	s_cmpk_lt_i32 s2, 0x680
	s_mov_b32 s88, 0x2f800000
	v_writelane_b32 v253, s1, 18
	s_cselect_b64 s[0:1], -1, 0
	v_writelane_b32 v253, s0, 19
	s_ashr_i32 s61, s30, 31
	s_mov_b32 s94, 0x3a000000
	v_writelane_b32 v253, s1, 20
	s_cmp_lt_u32 s2, 0x80
	s_cselect_b32 s100, 0x600, 0
	s_add_i32 s100, s100, s2
	s_mul_hi_i32 s0, s100, 0x4ec4ec4f
	s_lshr_b32 s1, s0, 31
	s_lshr_b32 s0, s0, 9
	s_add_i32 s0, s0, s1
	s_mulk_i32 s0, 0x680
	s_sub_i32 s0, s100, s0
	s_sext_i32_i16 s1, s0
	s_bfe_u32 s1, s1, 0x3001c
	s_add_i32 s1, s0, s1
	s_sext_i32_i16 s4, s1
	s_and_b32 s1, s1, 0xfff8
	s_ashr_i32 s4, s4, 3
	s_sub_i32 s0, s0, s1
	s_add_u32 s34, s28, 0x22e00000
	s_addc_u32 s35, s29, 0
	s_add_u32 s96, s28, 0x12800000
	s_addc_u32 s97, s29, 0
	s_lshl_b32 s59, s30, 9
	s_cmpk_lt_i32 s2, 0x300
	s_mul_hi_i32 s1, s2, 0x2aaaaaab
	s_cselect_b64 s[6:7], -1, 0
	s_lshr_b32 s5, s1, 31
	s_lshr_b32 s1, s1, 7
	s_add_i32 s1, s1, s5
	s_mulk_i32 s1, 0x300
	s_sub_i32 s1, s2, s1
	s_bfe_u32 s5, s1, 0x3001c
	v_writelane_b32 v253, s6, 21
	s_add_i32 s5, s1, s5
	s_mov_b32 s60, 0x3dd53b94
	v_writelane_b32 v253, s7, 22
	s_sext_i32_i16 s6, s5
	s_and_b32 s5, s5, 0xfff8
	s_ashr_i32 s6, s6, 3
	s_sub_i32 s1, s1, s5
	s_cmpk_lt_i32 s2, 0x400
	s_cselect_b64 s[8:9], -1, 0
	s_lshr_b32 s5, s3, 22
	s_add_i32 s5, s2, s5
	s_and_b32 s5, s5, 0xfc00
	s_sub_i32 s5, s2, s5
	s_sext_i32_i16 s7, s5
	s_bfe_u32 s7, s7, 0x3001c
	v_writelane_b32 v253, s8, 23
	s_add_i32 s7, s5, s7
	s_mov_b32 s62, 0x3fd744fd
	v_writelane_b32 v253, s9, 24
	s_sext_i32_i16 s8, s7
	s_and_b32 s7, s7, 0xfff8
	s_sub_i32 s5, s5, s7
	s_sext_i32_i16 s7, s5
	s_ashr_i32 s8, s8, 3
	s_lshl_b32 s9, s7, 7
	s_cmpk_lg_i32 s30, 0x100
	s_cselect_b64 s[10:11], -1, 0
	v_writelane_b32 v253, s10, 25
	s_cmpk_lt_i32 s2, 0x800
	s_mov_b32 s52, 0
	v_writelane_b32 v253, s11, 26
	s_cselect_b64 s[10:11], -1, 0
	s_lshr_b32 s5, s3, 24
	s_add_i32 s5, s2, s5
	s_ashr_i32 s16, s5, 8
	s_and_b32 s5, s5, 0xff00
	s_sub_i32 s5, s2, s5
	v_writelane_b32 v253, s10, 27
	s_ashr_i32 s17, s16, 31
	s_sext_i32_i16 s12, s5
	v_writelane_b32 v253, s11, 28
	s_bfe_u32 s12, s12, 0x3001c
	s_lshl_b64 s[10:11], s[16:17], 8
	s_add_i32 s12, s5, s12
	v_writelane_b32 v253, s10, 29
	s_sext_i32_i16 s13, s12
	s_and_b32 s12, s12, 0xfff8
	v_writelane_b32 v253, s11, 30
	s_mov_b32 s10, s16
	s_sub_i32 s12, s5, s12
	v_writelane_b32 v253, s10, 31
	s_ashr_i32 s13, s13, 3
	s_lshl_b32 s14, s12, 5
	v_writelane_b32 v253, s11, 32
	s_lshl_b64 s[10:11], s[16:17], 17
	s_add_u32 s54, s28, 0x1ee00000
	s_addc_u32 s55, s29, 0
	s_add_u32 s66, s28, 0x26e00000
	v_writelane_b32 v253, s10, 33
	s_addc_u32 s67, s29, 0
	s_waitcnt lgkmcnt(0)
	v_writelane_b32 v253, s11, 34
	s_add_u32 s10, s28, 0x3ce00000
	s_addc_u32 s11, s29, 0
	v_writelane_b32 v253, s10, 35
	s_cmpk_lt_i32 s2, 0x230
	s_barrier
	v_writelane_b32 v253, s11, 36
	s_cselect_b64 s[10:11], -1, 0
	v_writelane_b32 v253, s10, 37
	s_cmpk_lt_i32 s2, 0x200
	s_nop 0
	v_writelane_b32 v253, s11, 38
	s_cselect_b64 s[10:11], -1, 0
	v_writelane_b32 v253, s10, 39
	s_nop 1
	v_writelane_b32 v253, s11, 40
	s_add_u32 s10, s28, 0xe800000
	s_addc_u32 s11, s29, 0
	v_writelane_b32 v253, s10, 41
	s_add_i32 s5, s2, 0x230
	s_cmpk_lt_i32 s5, 0x330
	v_writelane_b32 v253, s11, 42
	v_writelane_b32 v253, s5, 43
	s_cselect_b64 s[10:11], -1, 0
	v_writelane_b32 v253, s10, 44
	s_cmpk_lt_i32 s2, 0x1000
	s_nop 0
	v_writelane_b32 v253, s11, 45
	s_cselect_b64 s[10:11], -1, 0
	s_lshr_b32 s5, s3, 20
	s_add_i32 s5, s2, s5
	s_and_b32 s5, s5, 0xf000
	s_sub_i32 s5, s2, s5
	s_sext_i32_i16 s15, s5
	s_bfe_u32 s15, s15, 0x3001c
	s_add_i32 s15, s5, s15
	s_and_b32 s16, s15, 0xfff8
	v_writelane_b32 v253, s10, 46
	s_sub_i32 s16, s5, s16
	s_sext_i32_i16 s5, s15
	v_writelane_b32 v253, s11, 47
	s_ashr_i32 s15, s5, 3
	s_lshl_b32 s17, s16, 9
	s_add_i32 s5, s2, 0x330
	v_writelane_b32 v253, s5, 48
	s_cmpk_lt_i32 s5, 0x730
	s_sext_i32_i16 s5, s0
	s_cselect_b64 s[10:11], -1, 0
	s_cmp_lt_i32 s5, 0
	s_movk_i32 s5, 0xd1
	s_cselect_b32 s5, s5, 0xd0
	s_mul_i32 s0, s5, s0
	s_add_i32 s0, s0, s4
	s_sext_i32_i16 s4, s0
	s_mulk_i32 s4, 0x4ec5
	s_lshr_b32 s5, s4, 31
	s_ashr_i32 s4, s4, 21
	s_add_i32 s4, s4, s5
	s_mul_i32 s5, s4, 0x68
	s_sub_i32 s0, s0, s5
	s_bfe_i32 s5, s0, 0x80000
	s_bfe_u32 s5, s5, 0x3000c
	s_add_i32 s5, s0, s5
	s_and_b32 s18, s5, 0xf8
	s_sub_i32 s0, s0, s18
	s_sext_i32_i16 s4, s4
	s_bfe_i32 s5, s5, 0x80000
	v_writelane_b32 v253, s10, 49
	s_lshl_b32 s4, s4, 3
	s_sext_i32_i16 s5, s5
	s_sext_i32_i8 s0, s0
	v_writelane_b32 v253, s11, 50
	s_add_i32 s10, s4, s0
	s_ashr_i32 s0, s5, 3
	s_sext_i32_i16 s4, s1
	v_writelane_b32 v253, s0, 51
	s_lshr_b32 s0, s5, 3
	s_cmp_lt_i32 s4, 0
	s_movk_i32 s4, 0x61
	s_cselect_b32 s4, s4, 0x60
	s_mul_i32 s1, s4, s1
	s_add_i32 s1, s1, s6
	s_sext_i32_i16 s4, s1
	s_mulk_i32 s4, 0x2aab
	s_lshr_b32 s5, s4, 31
	s_ashr_i32 s4, s4, 19
	s_add_i32 s4, s4, s5
	s_mul_i32 s5, s4, 48
	s_sub_i32 s1, s1, s5
	s_bfe_i32 s5, s1, 0x80000
	s_bfe_u32 s5, s5, 0x3000c
	s_add_i32 s5, s1, s5
	s_and_b32 s6, s5, 0xf8
	s_sub_i32 s1, s1, s6
	s_sext_i32_i16 s4, s4
	s_bfe_i32 s5, s5, 0x80000
	s_lshl_b32 s4, s4, 3
	s_sext_i32_i16 s5, s5
	s_sext_i32_i8 s1, s1
	s_add_i32 s18, s4, s1
	s_lshr_b32 s4, s5, 3
	s_ashr_i32 s1, s5, 3
	s_bfe_i64 s[4:5], s[4:5], 0x100000
	v_writelane_b32 v253, s1, 52
	s_lshl_b64 s[4:5], s[4:5], 18
	v_writelane_b32 v253, s4, 53
	s_ashr_i32 s19, s18, 31
	s_nop 0
	v_writelane_b32 v253, s5, 54
	s_mov_b32 s4, s18
	v_writelane_b32 v253, s4, 55
	s_nop 1
	v_writelane_b32 v253, s5, 56
	s_lshl_b64 s[4:5], s[18:19], 18
	s_cmp_lt_i32 s7, 0
	s_mulk_i32 s7, 0x81
	s_cselect_b32 s1, s7, s9
	v_writelane_b32 v253, s4, 57
	s_add_i32 s1, s8, s1
	s_nop 0
	v_writelane_b32 v253, s5, 58
	s_sext_i32_i16 s4, s1
	s_lshr_b32 s6, s4, 15
	s_bfe_u32 s4, s6, 0x6000a
	s_add_i32 s4, s1, s4
	s_and_b32 s5, s4, 0xffc0
	s_sub_i32 s5, s1, s5
	s_bfe_i32 s7, s5, 0x80000
	s_bfe_u32 s7, s7, 0x3000c
	s_add_i32 s7, s5, s7
	s_and_b32 s8, s7, 0xf8
	s_sext_i32_i16 s4, s4
	s_sub_i32 s5, s5, s8
	s_ashr_i32 s4, s4, 6
	s_bfe_i32 s7, s7, 0x80000
	s_lshl_b32 s4, s4, 3
	s_sext_i32_i16 s7, s7
	s_sext_i32_i8 s5, s5
	s_add_i32 s18, s4, s5
	s_ashr_i32 s4, s7, 3
	v_writelane_b32 v253, s4, 59
	s_lshr_b32 s4, s7, 3
	s_bfe_i64 s[4:5], s[4:5], 0x100000
	s_lshl_b64 s[4:5], s[4:5], 18
	v_writelane_b32 v253, s4, 60
	s_mov_b32 s8, s18
	s_ashr_i32 s19, s18, 31
	v_writelane_b32 v253, s5, 61
	v_writelane_b32 v253, s8, 62
	s_sext_i32_i16 s4, s12
	s_mul_i32 s12, s12, 33
	v_writelane_b32 v253, s9, 63
	s_lshl_b64 s[8:9], s[18:19], 18
	s_cmp_lt_i32 s4, 0
	s_cselect_b32 s4, s12, s14
	s_add_i32 s4, s4, s13
	s_sext_i32_i16 s5, s4
	s_bfe_u32 s5, s5, 0x4001b
	s_add_i32 s5, s4, s5
	s_and_b32 s7, s5, 0xfff0
	s_sub_i32 s4, s4, s7
	s_bfe_i32 s7, s4, 0x80000
	s_bfe_u32 s7, s7, 0x3000c
	v_writelane_b32 v254, s8, 0
	s_add_i32 s7, s4, s7
	s_sext_i32_i16 s5, s5
	v_writelane_b32 v254, s9, 1
	s_and_b32 s8, s7, 0xf8
	s_sub_i32 s4, s4, s8
	s_bfe_u32 s6, s6, 0x5000b
	s_ashr_i32 s5, s5, 4
	s_bfe_i32 s7, s7, 0x80000
	s_add_i32 s6, s1, s6
	s_lshl_b32 s5, s5, 3
	s_sext_i32_i16 s7, s7
	s_sext_i32_i8 s4, s4
	s_and_b32 s8, s6, 0xffe0
	s_add_i32 s12, s5, s4
	s_ashr_i32 s4, s7, 3
	s_sub_i32 s1, s1, s8
	v_writelane_b32 v254, s4, 2
	s_lshr_b32 s4, s7, 3
	s_bfe_i32 s8, s1, 0x80000
	s_bfe_i64 s[4:5], s[4:5], 0x100000
	s_bfe_u32 s8, s8, 0x2000d
	s_lshl_b64 s[4:5], s[4:5], 16
	s_add_i32 s8, s1, s8
	v_writelane_b32 v254, s4, 3
	s_and_b32 s9, s8, 0xfc
	s_sub_i32 s1, s1, s9
	v_writelane_b32 v254, s5, 4
	s_sext_i32_i16 s4, s6
	s_ashr_i32 s4, s4, 5
	s_bfe_i32 s5, s8, 0x80000
	s_lshl_b32 s4, s4, 2
	s_sext_i32_i16 s5, s5
	s_sext_i32_i8 s1, s1
	s_add_i32 s8, s4, s1
	s_ashr_i32 s4, s5, 2
	v_writelane_b32 v254, s4, 5
	s_mov_b32 s6, s12
	s_ashr_i32 s13, s12, 31
	v_writelane_b32 v254, s6, 6
	s_sext_i32_i16 s1, s16
	s_lshr_b32 s4, s5, 2
	v_writelane_b32 v254, s7, 7
	s_lshl_b64 s[6:7], s[12:13], 19
	s_cmp_lt_i32 s1, 0
	s_mulk_i32 s16, 0x201
	s_cselect_b32 s1, s16, s17
	s_add_i32 s1, s1, s15
	s_sext_i32_i16 s5, s1
	s_bfe_u32 s5, s5, 0x80017
	v_writelane_b32 v254, s6, 8
	s_add_i32 s5, s1, s5
	s_nop 0
	v_writelane_b32 v254, s7, 9
	s_and_b32 s6, s5, 0xff00
	s_sub_i32 s1, s1, s6
	s_sext_i32_i16 s6, s1
	s_bfe_u32 s6, s6, 0x3001c
	s_add_i32 s6, s1, s6
	s_and_b32 s7, s6, 0xfff8
	s_sext_i32_i16 s5, s5
	s_sub_i32 s1, s1, s7
	s_ashr_i32 s5, s5, 8
	s_lshl_b32 s5, s5, 3
	s_sext_i32_i16 s6, s6
	s_sext_i32_i16 s1, s1
	s_add_i32 s12, s5, s1
	s_ashr_i32 s1, s6, 3
	s_lshr_b32 s6, s6, 3
	s_bfe_i64 s[6:7], s[6:7], 0x100000
	v_writelane_b32 v254, s1, 10
	s_lshl_b64 s[6:7], s[6:7], 20
	v_writelane_b32 v254, s6, 11
	s_ashr_i32 s13, s12, 31
	s_mul_i32 s5, s31, s56
	v_writelane_b32 v254, s7, 12
	s_mov_b32 s6, s12
	v_writelane_b32 v254, s6, 13
	s_mov_b32 s31, 0x8000
	s_nop 0
	v_writelane_b32 v254, s7, 14
	s_lshl_b64 s[6:7], s[12:13], 20
	s_add_u32 s6, s28, s6
	s_addc_u32 s7, s29, s7
	s_add_u32 s12, s6, 0x80000
	v_writelane_b32 v254, s6, 15
	s_addc_u32 s13, s7, 0
	s_bfe_i64 s[0:1], s[0:1], 0x100000
	v_writelane_b32 v254, s7, 16
	v_writelane_b32 v254, s12, 17
	s_lshl_b64 s[0:1], s[0:1], 20
	s_ashr_i32 s11, s10, 31
	v_writelane_b32 v254, s13, 18
	v_writelane_b32 v254, s0, 19
	s_nop 1
	v_writelane_b32 v254, s1, 20
	s_mov_b32 s0, s10
	v_writelane_b32 v254, s0, 21
	s_nop 1
	v_writelane_b32 v254, s1, 22
	s_lshl_b64 s[0:1], s[10:11], 20
	s_add_u32 s0, s28, s0
	s_addc_u32 s1, s29, s1
	v_writelane_b32 v254, s5, 23
	s_add_u32 s6, s0, 0x80000
	v_writelane_b32 v254, s0, 24
	s_addc_u32 s7, s1, 0
	s_ashr_i32 s9, s8, 31
	v_writelane_b32 v254, s1, 25
	v_writelane_b32 v254, s6, 26
	s_bfe_i64 s[0:1], s[4:5], 0x100000
	s_lshl_b64 s[4:5], s[0:1], 20
	v_writelane_b32 v254, s7, 27
	v_writelane_b32 v254, s4, 28
	s_lshl_b64 s[0:1], s[0:1], 22
	s_mov_b64 s[10:11], 0x4000
	v_writelane_b32 v254, s5, 29
	v_writelane_b32 v254, s0, 30
	s_mov_b32 s5, 0
	s_nop 0
	v_writelane_b32 v254, s1, 31
	s_lshl_b32 s0, s2, 7
	s_add_i32 s1, s0, 0x39840
	v_writelane_b32 v254, s1, 32
	s_add_i32 s1, s0, 0xfffff400
	v_writelane_b32 v254, s1, 33
	s_add_i32 s1, s0, 0x10c00
	v_writelane_b32 v254, s1, 34
	s_add_i32 s0, s0, 0x18c00
	v_writelane_b32 v254, s0, 35
	v_readlane_b32 s0, v252, 38
	s_add_i32 s1, s0, 0x3980
	v_writelane_b32 v254, s1, 36
	s_lshl_b32 s1, s2, 1
	v_writelane_b32 v254, s1, 37
	s_addk_i32 s1, 0x800
	v_writelane_b32 v254, s1, 38
	s_lshl_b32 s1, s2, 12
	v_writelane_b32 v254, s1, 39
	s_lshl_b32 s1, s30, 12
	v_writelane_b32 v254, s1, 40
	s_add_i32 s1, s0, 0x1180
	v_writelane_b32 v254, s1, 41
	s_addk_i32 s0, 0x1980
	v_writelane_b32 v254, s0, 42
	s_add_i32 s0, 0, 0x20004
	v_writelane_b32 v254, s0, 43
	s_lshl_b64 s[0:1], s[8:9], 20
	v_writelane_b32 v254, s0, 44
	s_nop 1
	v_writelane_b32 v254, s1, 45
	s_mov_b32 s0, s8
	v_writelane_b32 v254, s0, 46
	s_nop 1
	v_writelane_b32 v254, s1, 47
	s_lshl_b64 s[0:1], s[8:9], 22
	v_writelane_b32 v254, s0, 48
	s_nop 1
	v_writelane_b32 v254, s1, 49
	v_writelane_b32 v254, s4, 50
	s_nop 1
	v_writelane_b32 v254, s5, 51
	v_writelane_b32 v255, s18, 0
	v_writelane_b32 v254, s6, 52
	v_writelane_b32 v255, s19, 1
	v_writelane_b32 v254, s7, 53
	v_writelane_b32 v255, s59, 2
	v_writelane_b32 v254, s8, 54
	v_writelane_b32 v255, s96, 3
	v_writelane_b32 v254, s9, 55
	v_writelane_b32 v254, s10, 56
	v_writelane_b32 v255, s97, 4
	v_writelane_b32 v255, s54, 5
	v_writelane_b32 v254, s11, 57
	v_writelane_b32 v254, s12, 58
	v_writelane_b32 v255, s55, 6
	v_writelane_b32 v255, s66, 7
	v_writelane_b32 v254, s13, 59
	v_writelane_b32 v254, s14, 60
	v_writelane_b32 v255, s67, 8
	v_writelane_b32 v255, s38, 9
	v_writelane_b32 v254, s15, 61
	v_writelane_b32 v254, s16, 62
	v_writelane_b32 v255, s39, 10
	v_writelane_b32 v255, s34, 11
	v_writelane_b32 v254, s17, 63
	s_nop 0
	v_writelane_b32 v255, s35, 12
	s_branch .LBB0_259

.LBB0_374:
	s_add_i32 s27, s27, 1
	s_cmp_lt_u32 s2, 0x80
	s_cselect_b32 s100, 1, 0
	s_sub_i32 s100, s27, s100
	s_cmp_ge_u32 s27, 7
	s_cselect_b32 s100, 7, s100
	s_mul_i32 s4, s100, s61
	s_mul_hi_u32 s5, s100, s30
	s_add_i32 s5, s5, s4
	s_mul_i32 s4, s100, s30
	s_add_u32 s14, s4, s2
	s_addc_u32 s15, s5, s3
	v_mov_b64_e32 v[0:1], 0x67f
	v_cmp_gt_i64_e64 s[4:5], s[14:15], v[0:1]
	s_and_b64 vcc, exec, s[4:5]
	s_cbranch_vccnz .LBB0_376
	s_mul_i32 s68, s15, 0xc4ec4ec5
	s_mul_hi_u32 s72, s14, 0xc4ec4ec5
	s_mul_hi_u32 s67, s15, 0xc4ec4ec5
	s_add_u32 s68, s68, s72
	s_mul_i32 s47, s14, 0x4ec4ec4e
	s_addc_u32 s67, s67, 0
	s_mul_hi_u32 s46, s14, 0x4ec4ec4e
	s_add_u32 s47, s47, s68
	s_addc_u32 s46, s46, 0
	s_add_u32 s46, s67, s46
	s_addc_u32 s47, 0, 0
	s_mul_i32 s68, s15, 0x4ec4ec4e
	s_mul_hi_u32 s67, s15, 0x4ec4ec4e
	s_add_u32 s46, s68, s46
	s_addc_u32 s47, s67, s47
	s_ashr_i32 s67, s15, 31
	s_mul_i32 s68, s67, 0x4ec4ec4e
	s_mul_hi_u32 s72, s67, 0xc4ec4ec5
	s_add_i32 s68, s72, s68
	s_mul_i32 s67, s67, 0xc4ec4ec5
	s_add_i32 s68, s68, s67
	s_add_u32 s46, s46, s67
	s_addc_u32 s47, s47, s68
	s_ashr_i64 s[72:73], s[46:47], 9
	s_lshr_b32 s46, s47, 31
	s_add_u32 s46, s72, s46
	s_mulk_i32 s46, 0x680
	s_sub_i32 s46, s14, s46
	s_sext_i32_i16 s47, s46
	s_bfe_u32 s47, s47, 0x3001c
	s_add_i32 s47, s46, s47
	s_sext_i32_i16 s67, s47
	s_and_b32 s47, s47, 0xfff8
	s_sub_i32 s46, s46, s47
	s_ashr_i32 s67, s67, 3
	s_sext_i32_i16 s47, s46
	s_cmp_lt_i32 s47, 0
	s_movk_i32 s39, 0xd1
	s_cselect_b32 s47, s39, 0xd0
	s_mul_i32 s46, s46, s47
	s_add_i32 s46, s46, s67
	s_sext_i32_i16 s47, s46
	s_mulk_i32 s47, 0x4ec5
	s_lshr_b32 s67, s47, 31
	s_ashr_i32 s47, s47, 21
	s_add_i32 s47, s47, s67
	s_lshl_b32 s67, s47, 3
	s_mulk_i32 s47, 0x68
	s_sub_i32 s46, s46, s47
	s_bfe_i32 s47, s46, 0x80000
	s_bfe_u32 s47, s47, 0x3000c
	s_add_i32 s47, s46, s47
	s_bfe_i32 s68, s47, 0x80000
	s_and_b32 s47, s47, 0xf8
	s_sub_i32 s46, s46, s47
	s_sext_i32_i16 s68, s68
	s_sext_i32_i8 s46, s46
	s_add_i32 s72, s67, s46
	s_ashr_i32 s74, s68, 3
